# combination: unmasked staging + hoisted invariants + early first LDS reads + 64-bit accumulator clears + XGEN bump before the leader's acquire
# speedup vs baseline: 1.0011x; 1.0011x over previous
.LBB0_361:
	v_lshrrev_b32_e32 v15, 3, v0
	v_and_b32_e32 v16, 7, v0
	v_lshlrev_b32_e32 v16, 4, v16
	v_mad_u32_u24 v196, v15, s95, v16
	v_and_b32_e32 v16, 48, v0
	v_mad_u32_u24 v198, v17, s95, v16
	s_lshl_b32 s60, s95, 6
	s_lshl_b32 s61, s95, 4
	s_sub_i32 s93, 4, s92
	s_max_i32 s93, s93, 0
	s_cmp_eq_u32 s17, 0
	s_cselect_b32 s93, 0, s93
	v_mov_b64_e32 v[138:139], 0
	v_mov_b64_e32 v[140:141], 0
	v_mov_b64_e32 v[118:119], 0
	v_mov_b64_e32 v[120:121], 0
	v_mov_b64_e32 v[134:135], 0
	v_mov_b64_e32 v[136:137], 0
	v_mov_b64_e32 v[130:131], 0
	v_mov_b64_e32 v[132:133], 0
	v_mov_b64_e32 v[126:127], 0
	v_mov_b64_e32 v[128:129], 0
	v_mov_b64_e32 v[122:123], 0
	v_mov_b64_e32 v[124:125], 0
	v_mov_b64_e32 v[114:115], 0
	v_mov_b64_e32 v[116:117], 0
	v_mov_b64_e32 v[106:107], 0
	v_mov_b64_e32 v[108:109], 0
	v_mov_b64_e32 v[110:111], 0
	v_mov_b64_e32 v[112:113], 0
	v_mov_b64_e32 v[102:103], 0
	v_mov_b64_e32 v[104:105], 0
	s_waitcnt lgkmcnt(8)
	v_mfma_f32_16x16x32_bf16 v[150:153], v[178:181], v[74:77], v[66:69]
	v_mfma_f32_16x16x32_bf16 v[154:157], v[186:189], v[74:77], v[66:69]
	v_mfma_f32_16x16x32_bf16 v[162:165], v[186:189], v[82:85], v[66:69]
	v_mfma_f32_16x16x32_bf16 v[150:153], v[182:185], v[70:73], v[150:153]
	v_mfma_f32_16x16x32_bf16 v[154:157], v[190:193], v[70:73], v[154:157]
	v_mfma_f32_16x16x32_bf16 v[162:165], v[190:193], v[78:81], v[162:165]
	s_waitcnt lgkmcnt(0)
	ds_read_b128 v[178:181], v194 offset:4608
	ds_read_b128 v[182:185], v194 offset:4672
	ds_read_b128 v[186:189], v194 offset:6912
	ds_read_b128 v[190:193], v194 offset:6976
	ds_read_b64_tr_b16 v[216:217], v195 offset:4608
	ds_read_b64_tr_b16 v[218:219], v195 offset:6912
	ds_read_b64_tr_b16 v[220:221], v195 offset:4640
	ds_read_b64_tr_b16 v[222:223], v195 offset:6944
	ds_read_b64_tr_b16 v[224:225], v195 offset:4672
	ds_read_b64_tr_b16 v[226:227], v195 offset:6976
	ds_read_b64_tr_b16 v[228:229], v195 offset:4704
	ds_read_b64_tr_b16 v[230:231], v195 offset:7008
